# baseline (speedup 1.0000x reference)
; __device__ void attn_item(const Params& p, int l, int b, int h, int qb, char* smem) {
;     const int tid = opaque_tid(), lane = tid & 63, w = tid >> 6;
;     const int r = lane & 15, g4 = lane >> 4;
;     char* Ks = smem; char* Vt = smem + 16384; float* ckl = (float*)(smem + 32768);
;     const int q0 = qb * 128;
;     const int nkeys = q0 + 128;
;     const int nkt = nkeys >> 6;
;     const int bh = b * 16 + h;
;     uint2 gpre[2][4];
; #pragma unroll
;     for (int qt = 0; qt < 2; ++qt)
; #pragma unroll
;         for (int dt = 0; dt < 4; ++dt)
;             gpre[qt][dt] = *(const uint2*)(p.gb + (size_t)(b * 2048 + q0 + 32 * w + 16 * qt + r) * 1024 + h * 64 + 16 * dt + 4 * g4);
;     bf16x8 qf[2][2];
; #pragma unroll
;     for (int qt = 0; qt < 2; ++qt)
; #pragma unroll
;         for (int ks = 0; ks < 2; ++ks)
;             qf[qt][ks] = *(const bf16x8*)(p.qb + (size_t)(b * 2048 + q0 + 32 * w + 16 * qt + r) * 1024 + h * 64 + ks * 32 + g4 * 8);
;     f32x4 o[4][2];
; #pragma unroll
;     for (int dt = 0; dt < 4; ++dt)
; #pragma unroll
;         for (int qt = 0; qt < 2; ++qt) o[dt][qt] = (f32x4){0.f, 0.f, 0.f, 0.f};
;     float mrun[2] = {-INFINITY, -INFINITY}, lrun[2] = {0.f, 0.f};
;     const int lrow = tid >> 3, lkc = tid & 7;
;     const u16* kp = p.kb + (size_t)(b * 2048 + lrow) * 1024 + h * 64 + lkc * 8;
;     const u16* vp = p.vT + ((size_t)(bh * 64 + lrow)) * 2048 + lkc * 8;
;     const int lds_w = lrow * 128 + ((lkc ^ (lrow & 7)) << 4);
;     uint4 rk0, rk1, rv0, rv1;
;     ...
;     AL(nkt - 1);
;     {
;         float tot[16];
;         const float4* ct = (const float4*)(p.ctot + bh * 16);
; #pragma unroll
;         for (int i = 0; i < 4; ++i) { float4 v = ct[i]; tot[4 * i] = v.x; tot[4 * i + 1] = v.y; tot[4 * i + 2] = v.z; tot[4 * i + 3] = v.w; }
;         const int half = tid >> 7, tl = tid & 127;
;         float base = half ? tot[0] : 0.f;
; #pragma unroll
;         for (int jj = 0; jj < 8; ++jj) {
;             const int tile = 2 * jj + half;
;             if (tile <= qb) ckl[tile * 128 + tl] = (base + p.clT[(size_t)bh * 2048 + tile * 128 + tl]) * LOG2E;
;             base += tot[2 * jj + half] + tot[(2 * jj + half + 1) & 15];
;         }
;     }
;     ...
;     const float s_bound = sqrtf(fmaxf(fmaxf(red[0], red[1]), fmaxf(red[2], red[3]))) * __uint_as_float(p.knmax[l * 256 + bh]) * sl2 * 1.02f;
.LBB0_466:
	s_or_b64 exec, exec, s[0:1]
	s_cmpk_gt_i32 s52, 0x7f
	s_cbranch_scc0 .LBB0_521
	s_cmpk_gt_u32 s52, 0x37f
	s_cbranch_scc0 .LBB0_522
	s_add_i32 s0, s52, 0xfffffc80
	s_lshr_b32 s4, s0, 8
	s_sub_i32 s6, 15, s4
	s_bfe_u32 s0, s0, 0x40004
	v_mov_b32_e32 v54, v141
	s_lshl_b32 s5, s6, 7
	s_lshl_b32 s10, s0, 11
	s_lshl_b32 s7, s0, 4
	v_ashrrev_i32_e32 v58, 6, v54
	v_and_b32_e32 v55, 15, v54
	s_or_b32 s0, s5, s10
	v_lshlrev_b32_e32 v57, 5, v58
	v_or_b32_e32 v0, s0, v55
	s_and_b32 s8, s52, 15
	v_add_u32_e32 v2, v0, v57
	v_readlane_b32 s12, v214, 50
	s_lshl_b32 s2, s8, 7
	v_readlane_b32 s20, v214, 58
	v_ashrrev_i32_e32 v3, 31, v2
	v_bfe_u32 v56, v54, 4, 2
	v_readlane_b32 s21, v214, 59
	s_add_u32 s0, s20, s2
	v_lshlrev_b64 v[126:127], 11, v[2:3]
	v_or_b32_e32 v2, 16, v2
	s_addc_u32 s1, s21, 0
	v_lshlrev_b32_e32 v0, 3, v56
	v_ashrrev_i32_e32 v3, 31, v2
	v_readlane_b32 s14, v214, 52
	v_lshl_add_u64 v[4:5], s[0:1], 0, v[0:1]
	v_lshlrev_b64 v[116:117], 11, v[2:3]
	v_readlane_b32 s15, v214, 53
	v_lshl_add_u64 v[6:7], v[4:5], 0, v[126:127]
	v_lshl_add_u64 v[2:3], v[4:5], 0, v[116:117]
	s_add_u32 s0, s14, s2
	global_load_dwordx2 v[128:129], v[6:7], off
	global_load_dwordx2 v[124:125], v[6:7], off offset:32
	global_load_dwordx2 v[122:123], v[6:7], off offset:64
	global_load_dwordx2 v[120:121], v[6:7], off offset:96
	global_load_dwordx2 v[118:119], v[2:3], off
	global_load_dwordx2 v[114:115], v[2:3], off offset:32
	global_load_dwordx2 v[112:113], v[2:3], off offset:64
	global_load_dwordx2 v[110:111], v[2:3], off offset:96
	s_addc_u32 s1, s15, 0
	v_and_b32_e32 v2, 48, v54
	v_mov_b32_e32 v3, v1
	v_lshl_add_u64 v[2:3], s[0:1], 0, v[2:3]
	v_lshl_add_u64 v[8:9], v[2:3], 0, v[126:127]
	v_lshl_add_u64 v[2:3], v[2:3], 0, v[116:117]
	v_ashrrev_i32_e32 v59, 3, v54
	global_load_dwordx4 v[4:7], v[8:9], off
	s_nop 0
	global_load_dwordx4 v[8:11], v[8:9], off offset:64
	s_nop 0
	global_load_dwordx4 v[12:15], v[2:3], off
	global_load_dwordx4 v[16:19], v[2:3], off offset:64
	v_add_u32_e32 v2, s10, v59
	v_ashrrev_i32_e32 v3, 31, v2
	v_readlane_b32 s16, v214, 54
	v_readlane_b32 s17, v214, 55
	v_lshlrev_b64 v[2:3], 11, v[2:3]
	s_or_b32 s9, s7, s8
	v_readlane_b32 s98, v212, 10
	v_readlane_b32 s100, v213, 18
	v_readlane_b32 s101, v213, 19
	s_or_b32 s98, s9, s98
	s_lshl_b32 s98, s98, 2
	s_add_u32 s100, s100, s98
	s_addc_u32 s101, s101, 0
	global_load_dword v226, v1, s[100:101]
	v_lshl_add_u64 v[2:3], s[16:17], 0, v[2:3]
	v_lshlrev_b32_e32 v20, 4, v54
	v_lshl_add_u64 v[2:3], v[2:3], 0, s[2:3]
	v_and_b32_e32 v20, 0x70, v20
	v_mov_b32_e32 v21, v1
	s_lshl_b32 s0, s9, 6
	v_lshl_add_u64 v[130:131], v[2:3], 0, v[20:21]
	v_add_u32_e32 v2, s0, v59
	v_ashrrev_i32_e32 v3, 31, v2
	v_readlane_b32 s18, v214, 56
	v_readlane_b32 s19, v214, 57
	v_lshlrev_b64 v[2:3], 12, v[2:3]
	s_or_b32 s1, s5, 64
	v_lshl_add_u64 v[2:3], s[18:19], 0, v[2:3]
	s_lshl_b32 s2, s1, 11
	v_lshl_add_u64 v[132:133], v[2:3], 0, v[20:21]
	v_lshl_add_u64 v[2:3], v[130:131], 0, s[2:3]
	s_lshl_b32 s2, s6, 18
	s_or_b32 s2, s2, 0x30000
	v_readlane_b32 s13, v214, 51
	v_readlane_b32 s22, v214, 60
	v_readlane_b32 s23, v214, 61
	v_readlane_b32 s24, v214, 62
	v_readlane_b32 s25, v214, 63
	v_readlane_b32 s26, v213, 0
	v_readlane_b32 s27, v213, 1
	v_lshl_add_u64 v[24:25], v[130:131], 0, s[2:3]
	s_lshl_b32 s2, s1, 1
	v_mov_b32_e32 v28, s0
	s_mov_b64 s[0:1], 0x20000
	v_readlane_b32 s12, v213, 4
	v_lshl_add_u64 v[134:135], v[132:133], 0, s[0:1]
	v_readlane_b32 s18, v213, 10
	v_readlane_b32 s19, v213, 11
	v_lshl_add_u64 v[32:33], v[134:135], 0, s[2:3]
	global_load_dwordx4 v[20:23], v[2:3], off
	s_nop 0
	global_load_dwordx4 v[24:27], v[24:25], off
	s_nop 0
	global_load_dwordx4 v[44:47], v28, s[18:19] offset:16
	global_load_dwordx4 v[48:51], v28, s[18:19]
	v_lshl_add_u64 v[2:3], v[132:133], 0, s[2:3]
	global_load_dwordx4 v[36:39], v28, s[18:19] offset:48
	global_load_dwordx4 v[40:43], v28, s[18:19] offset:32
	s_nop 0
	global_load_dwordx4 v[28:31], v[2:3], off
	s_nop 0
	global_load_dwordx4 v[32:35], v[32:33], off
	s_movk_i32 s0, 0x7f
	v_readlane_b32 s16, v213, 8
	v_cmp_lt_u32_e32 vcc, s0, v54
	s_lshl_b32 s0, s9, 13
	v_readlane_b32 s17, v213, 9
	v_lshlrev_b32_e32 v2, 2, v54
	s_add_u32 s0, s16, s0
	v_ashrrev_i32_e32 v60, 7, v54
	v_and_b32_e32 v2, 0x1fc, v2
	s_addc_u32 s1, s17, 0
	v_mov_b32_e32 v3, v1
	v_lshl_add_u64 v[52:53], s[0:1], 0, v[2:3]
	v_readlane_b32 s13, v213, 5
	v_readlane_b32 s14, v213, 6
	v_readlane_b32 s15, v213, 7
	v_readlane_b32 s20, v213, 12
	v_readlane_b32 s21, v213, 13
	v_readlane_b32 s22, v213, 14
	v_readlane_b32 s23, v213, 15
	v_readlane_b32 s24, v213, 16
	v_readlane_b32 s25, v213, 17
	v_readlane_b32 s26, v213, 18
	v_readlane_b32 s27, v213, 19
	s_waitcnt vmcnt(4)
	v_cndmask_b32_e32 v61, 0, v48, vcc
	v_cmp_ge_i32_e32 vcc, s6, v60
	s_and_saveexec_b64 s[0:1], vcc
	s_cbranch_execz .LBB0_470
	v_and_b32_e32 v62, 0xffffff80, v54
	v_ashrrev_i32_e32 v63, 31, v62
	v_lshl_add_u64 v[64:65], v[62:63], 2, v[52:53]
	global_load_dword v216, v[64:65], off
	global_load_dword v217, v[64:65], off offset:1024
	global_load_dword v218, v[64:65], off offset:2048
	global_load_dword v219, v[64:65], off offset:3072
	v_add_co_u32_e32 v224, vcc, 0x1000, v64
	s_nop 1
	v_addc_co_u32_e32 v225, vcc, 0, v65, vcc
	global_load_dword v220, v[224:225], off
	global_load_dword v221, v[224:225], off offset:1024
	global_load_dword v222, v[224:225], off offset:2048
	global_load_dword v223, v[224:225], off offset:3072
	v_lshl_or_b32 v62, v62, 2, v2
	s_waitcnt vmcnt(0)
	v_mov_b32_e32 v3, v216
	v_add_f32_e32 v3, v61, v3
	v_mul_f32_e32 v3, 0x3fb8aa3b, v3
	ds_write_b32 v62, v3 offset:32768

; __device__ void attn_item(const Params& p, int l, int b, int h, int qb, char* smem) {
;     ...
;     f32x4 o[4][2];
; #pragma unroll
;     for (int dt = 0; dt < 4; ++dt)
; #pragma unroll
;         for (int qt = 0; qt < 2; ++qt) o[dt][qt] = (f32x4){0.f, 0.f, 0.f, 0.f};
;     float mrun[2] = {-INFINITY, -INFINITY}, lrun[2] = {0.f, 0.f};
;     ...
;         float m2 = fmaxf(qn[0], qn[1]);
;         m2 = fmaxf(m2, __shfl_xor(m2, 1)); m2 = fmaxf(m2, __shfl_xor(m2, 2));
;         m2 = fmaxf(m2, __shfl_xor(m2, 4)); m2 = fmaxf(m2, __shfl_xor(m2, 8));
;         if (lane == 0) red[w] = m2;
;     }
;     __syncthreads();
;     const float sl2 = 0.125f * LOG2E;
;     const float s_bound = sqrtf(fmaxf(fmaxf(red[0], red[1]), fmaxf(red[2], red[3]))) * __uint_as_float(p.knmax[l * 256 + bh]) * sl2 * 1.02f;
;     float* red2 = red + 4;
;     float wmin_prev = -INFINITY;
;     const int qmax_w = q0 + 32 * w + 31;
.LBB0_486:
	s_or_b64 exec, exec, s[0:1]
	s_add_i32 s0, s5, 0x80
	s_lshr_b32 s15, s0, 6
	v_readlane_b32 s0, v212, 10
	s_or_b32 s2, s9, s0
	v_readlane_b32 s16, v213, 4
	s_lshl_b32 s14, s8, 6
	s_lshl_b64 s[0:1], s[2:3], 2
	v_readlane_b32 s30, v213, 18
	v_readlane_b32 s31, v213, 19
	s_add_u32 s0, s30, s0
	s_addc_u32 s1, s31, s1
	s_waitcnt lgkmcnt(0)
	s_barrier
	s_nop 0
	ds_read_b128 v[68:71], v1 offset:40960
	v_and_b32_e32 v36, 7, v54
	v_bitop3_b32 v37, v56, v54, 7 bitop3:0x78
	v_lshrrev_b32_e32 v38, 5, v2
	v_add_u32_e32 v183, s5, v57
	v_lshlrev_b32_e32 v184, 7, v55
	v_mov_b32_e32 v2, v1
	v_mov_b32_e32 v3, v1
	v_lshlrev_b32_e32 v188, 4, v37
	v_bitop3_b32 v37, v56, v36, 4 bitop3:0x36
	v_bitop3_b32 v39, v38, v54, 7 bitop3:0x78
	v_bitop3_b32 v40, v38, v36, 2 bitop3:0x36
	v_bitop3_b32 v41, v38, v36, 4 bitop3:0x36
	v_bitop3_b32 v36, v38, v36, 6 bitop3:0x36
	v_lshlrev_b32_e32 v177, 2, v56
	v_lshlrev_b32_e32 v185, 4, v56
	v_or_b32_e32 v136, v183, v55
	v_and_or_b32 v189, v0, 8, v184
	v_mov_b32_e32 v0, v1
	v_lshlrev_b32_e32 v190, 4, v37
	v_lshlrev_b32_e32 v191, 4, v39
	v_lshlrev_b32_e32 v192, 4, v40
	v_lshlrev_b32_e32 v193, 4, v41
	v_lshlrev_b32_e32 v194, 4, v36
	v_mov_b64_e32 v[42:43], v[2:3]
	v_mov_b64_e32 v[58:59], v[2:3]
	v_mov_b64_e32 v[46:47], v[2:3]
	v_mov_b64_e32 v[62:63], v[2:3]
	v_mov_b64_e32 v[50:51], v[2:3]
	v_mov_b64_e32 v[66:67], v[2:3]
	v_mov_b64_e32 v[54:55], v[2:3]
	v_mov_b64_e32 v[38:39], v[2:3]
	v_mov_b64_e32 v[40:41], v[0:1]
	v_mov_b64_e32 v[56:57], v[0:1]
	v_mov_b64_e32 v[44:45], v[0:1]
	v_mov_b64_e32 v[60:61], v[0:1]
	v_mov_b64_e32 v[48:49], v[0:1]
	v_mov_b64_e32 v[64:65], v[0:1]
	v_mov_b64_e32 v[52:53], v[0:1]
	v_mov_b64_e32 v[36:37], v[0:1]
	s_waitcnt lgkmcnt(0)
	v_max_f32_e32 v0, v71, v71
	v_max_f32_e32 v2, v70, v70
	v_max_f32_e32 v0, v2, v0
	v_max3_f32 v0, v68, v69, v0
	s_mov_b32 s1, 0xf800000
	v_mul_f32_e32 v2, 0x4f800000, v0
	v_cmp_gt_f32_e32 vcc, s1, v0
	v_readlane_b32 s17, v213, 5
	v_readlane_b32 s18, v213, 6
	v_cndmask_b32_e32 v0, v0, v2, vcc
	v_sqrt_f32_e32 v2, v0
	s_lshl_b32 s0, s4, 9
	s_lshl_b32 s1, s4, 7
	s_sub_i32 s18, 0x9efc, s0
	v_add_u32_e32 v3, -1, v2
	v_add_u32_e32 v68, 1, v2
	v_fma_f32 v69, -v3, v2, v0
	s_sub_i32 s17, 0x7ff, s1
	v_fma_f32 v70, -v68, v2, v0
	v_cmp_ge_f32_e64 s[0:1], 0, v69
	s_mov_b32 s16, 0
	v_mov_b32_e32 v175, 0
	v_cndmask_b32_e64 v2, v2, v3, s[0:1]
	v_cmp_lt_f32_e64 s[0:1], 0, v70
	v_mov_b32_e32 v195, 0xff800000
	v_mov_b32_e32 v196, 0xff800000
	v_cndmask_b32_e64 v2, v2, v68, s[0:1]
	v_mul_f32_e32 v3, 0x37800000, v2
	v_cndmask_b32_e32 v2, v2, v3, vcc
	v_cmp_class_f32_e32 vcc, v0, v155
	v_mov_b32_e32 v186, 0
	v_or_b32_e32 v187, 31, v183
	v_cndmask_b32_e32 v0, v2, v0, vcc
	v_or_b32_e32 v138, 16, v136
	v_mov_b32_e32 v137, v136
	v_add_u32_e32 v139, 13, v136
	v_add_u32_e32 v140, 14, v136
	v_mov_b32_e32 v2, 0xff800000
	v_readlane_b32 s19, v213, 7
	s_waitcnt vmcnt(0)
	v_mul_f32_e32 v0, v226, v0
	v_mul_f32_e32 v0, 0x3e38aa3b, v0
	v_mul_f32_e32 v0, 0x3f828f5c, v0
	v_readlane_b32 s20, v213, 8
	v_readlane_b32 s21, v213, 9
	v_readlane_b32 s22, v213, 10
	v_readlane_b32 s23, v213, 11
	v_readlane_b32 s24, v213, 12
	v_readlane_b32 s25, v213, 13
	v_readlane_b32 s26, v213, 14
	v_readlane_b32 s27, v213, 15
	v_readlane_b32 s28, v213, 16
	v_readlane_b32 s29, v213, 17
	s_branch .LBB0_488
